# v015 + nt (streaming) hint on the 16 output stores of the final rmsnorm phase (write-once data)
# speedup vs baseline: 1.0130x; 1.0059x over previous
; __global__ void __launch_bounds__(512, 2) fwd_megakernel(Args a) {
;     ...
;         for (int row = gw; row < MTOK; row += 2 * NGW) {
;             const int row2 = row + NGW; const bool has2 = row2 < MTOK; const int r2 = has2 ? row2 : row;
;             const u32x2* xr = (const u32x2*)(X1B + (size_t)row * DM); const u32x2* xq = (const u32x2*)(X1B + (size_t)r2 * DM);
;             f32x4* orow = (f32x4*)(a.out + (size_t)row * DM); f32x4* orow2 = (f32x4*)(a.out + (size_t)r2 * DM);
;             const float rs = __builtin_amdgcn_rsqf(ssq3[row] * (1.f / DM) + EPS), rt = __builtin_amdgcn_rsqf(ssq3[r2] * (1.f / DM) + EPS);
;             u32x2 w[8], z[8];
; #pragma unroll
;             for (int j = 0; j < 8; ++j) { w[j] = xr[lane + 64 * j]; z[j] = xq[lane + 64 * j]; }
; #pragma unroll
;             for (int j = 0; j < 8; ++j) { const f32x4 v = (f32x4){pg8::bf_lo(w[j].x), pg8::bf_hi(w[j].x), pg8::bf_lo(w[j].y), pg8::bf_hi(w[j].y)}; orow[lane + 64 * j] = v * rs * gv[j]; }
;             if (has2) {
; #pragma unroll
;                 for (int j = 0; j < 8; ++j) { const f32x4 v = (f32x4){pg8::bf_lo(z[j].x), pg8::bf_hi(z[j].x), pg8::bf_lo(z[j].y), pg8::bf_hi(z[j].y)}; orow2[lane + 64 * j] = v * rt * gv[j]; } }
.LBB0_1218:
	s_add_i32 s18, s52, s12
	s_cmp_lt_i32 s18, 0xc000
	s_cselect_b32 s10, s18, s12
	s_ashr_i32 s11, s10, 31
	s_lshl_b64 s[14:15], s[10:11], 2
	s_add_u32 s14, s6, s14
	global_load_dword v76, v33, s[0:1]
	global_load_dwordx2 v[62:63], v[38:39], off offset:-2048
	global_load_dwordx2 v[64:65], v[38:39], off offset:-1536
	global_load_dwordx2 v[66:67], v[38:39], off offset:-1024
	global_load_dwordx2 v[68:69], v[38:39], off offset:-512
	global_load_dwordx2 v[70:71], v[38:39], off
	global_load_dwordx2 v[72:73], v[38:39], off offset:512
	s_addc_u32 s15, s7, s15
	s_lshl_b64 s[16:17], s[10:11], 12
	v_lshl_add_u64 v[74:75], v[34:35], 0, s[16:17]
	global_load_dwordx2 v[86:87], v[38:39], off offset:1024
	global_load_dwordx2 v[88:89], v[38:39], off offset:1536
	global_load_dword v61, v33, s[14:15]
	global_load_dwordx2 v[54:55], v[74:75], off
	global_load_dwordx2 v[52:53], v[74:75], off offset:512
	global_load_dwordx2 v[50:51], v[74:75], off offset:1024
	global_load_dwordx2 v[48:49], v[74:75], off offset:1536
	global_load_dwordx2 v[46:47], v[74:75], off offset:2048
	global_load_dwordx2 v[44:45], v[74:75], off offset:2560
	global_load_dwordx2 v[42:43], v[74:75], off offset:3072
	global_load_dwordx2 v[40:41], v[74:75], off offset:3584
	v_add_co_u32_e32 v90, vcc, s13, v36
	s_cmp_gt_i32 s18, 0xbfff
	s_nop 0
	v_addc_co_u32_e32 v91, vcc, -1, v37, vcc
	s_waitcnt vmcnt(17)
	v_fmamk_f32 v85, v76, 0x3a000000, v32
	v_rsq_f32_e32 v92, v85
	s_waitcnt vmcnt(16)
	v_lshlrev_b32_e32 v74, 16, v62
	v_and_b32_e32 v75, 0xffff0000, v62
	v_lshlrev_b32_e32 v62, 16, v63
	v_and_b32_e32 v63, 0xffff0000, v63
	s_waitcnt vmcnt(15)
	v_lshlrev_b32_e32 v76, 16, v64
	v_and_b32_e32 v77, 0xffff0000, v64
	v_lshlrev_b32_e32 v64, 16, v65
	v_and_b32_e32 v65, 0xffff0000, v65
	s_waitcnt vmcnt(14)
	v_lshlrev_b32_e32 v78, 16, v66
	v_and_b32_e32 v79, 0xffff0000, v66
	v_lshlrev_b32_e32 v66, 16, v67
	v_and_b32_e32 v67, 0xffff0000, v67
	s_waitcnt vmcnt(13)
	v_lshlrev_b32_e32 v80, 16, v68
	v_and_b32_e32 v81, 0xffff0000, v68
	v_lshlrev_b32_e32 v68, 16, v69
	v_and_b32_e32 v69, 0xffff0000, v69
	s_waitcnt vmcnt(12)
	v_lshlrev_b32_e32 v82, 16, v70
	v_and_b32_e32 v83, 0xffff0000, v70
	v_lshlrev_b32_e32 v70, 16, v71
	v_and_b32_e32 v71, 0xffff0000, v71
	s_waitcnt vmcnt(11)
	v_lshlrev_b32_e32 v84, 16, v72
	v_and_b32_e32 v85, 0xffff0000, v72
	v_lshlrev_b32_e32 v72, 16, v73
	v_and_b32_e32 v73, 0xffff0000, v73
	v_pk_mul_f32 v[74:75], v[92:93], v[74:75] op_sel_hi:[0,1]
	v_pk_mul_f32 v[62:63], v[92:93], v[62:63] op_sel_hi:[0,1]
	v_pk_mul_f32 v[76:77], v[92:93], v[76:77] op_sel_hi:[0,1]
	v_pk_mul_f32 v[94:95], v[92:93], v[64:65] op_sel_hi:[0,1]
	v_pk_mul_f32 v[78:79], v[92:93], v[78:79] op_sel_hi:[0,1]
	v_pk_mul_f32 v[96:97], v[92:93], v[66:67] op_sel_hi:[0,1]
	v_pk_mul_f32 v[80:81], v[92:93], v[80:81] op_sel_hi:[0,1]
	v_pk_mul_f32 v[98:99], v[92:93], v[68:69] op_sel_hi:[0,1]
	v_pk_mul_f32 v[82:83], v[92:93], v[82:83] op_sel_hi:[0,1]
	v_pk_mul_f32 v[100:101], v[92:93], v[70:71] op_sel_hi:[0,1]
	v_pk_mul_f32 v[102:103], v[92:93], v[84:85] op_sel_hi:[0,1]
	v_pk_mul_f32 v[84:85], v[92:93], v[72:73] op_sel_hi:[0,1]
	v_pk_mul_f32 v[64:65], v[2:3], v[62:63]
	v_pk_mul_f32 v[62:63], v[0:1], v[74:75]
	v_pk_mul_f32 v[68:69], v[6:7], v[94:95]
	v_pk_mul_f32 v[66:67], v[4:5], v[76:77]
	v_pk_mul_f32 v[72:73], v[10:11], v[96:97]
	v_pk_mul_f32 v[70:71], v[8:9], v[78:79]
	v_pk_mul_f32 v[76:77], v[14:15], v[98:99]
	v_pk_mul_f32 v[74:75], v[12:13], v[80:81]
	v_pk_mul_f32 v[80:81], v[18:19], v[100:101]
	v_pk_mul_f32 v[78:79], v[16:17], v[82:83]
	v_pk_mul_f32 v[84:85], v[22:23], v[84:85]
	v_pk_mul_f32 v[82:83], v[20:21], v[102:103]
	global_store_dwordx4 v[90:91], v[62:65], off offset:-3072 nt
	global_store_dwordx4 v[90:91], v[66:69], off offset:-2048 nt
	global_store_dwordx4 v[90:91], v[70:73], off offset:-1024 nt
	global_store_dwordx4 v[36:37], v[74:77], off offset:-4096 nt
	global_store_dwordx4 v[36:37], v[78:81], off offset:-3072 nt
	global_store_dwordx4 v[36:37], v[82:85], off offset:-2048 nt
	s_waitcnt vmcnt(16)
	v_lshlrev_b32_e32 v62, 16, v86
	v_and_b32_e32 v63, 0xffff0000, v86
	v_lshlrev_b32_e32 v64, 16, v87
	v_and_b32_e32 v65, 0xffff0000, v87
	v_pk_mul_f32 v[62:63], v[92:93], v[62:63] op_sel_hi:[0,1]
	v_pk_mul_f32 v[64:65], v[92:93], v[64:65] op_sel_hi:[0,1]
	v_pk_mul_f32 v[64:65], v[26:27], v[64:65]
	v_pk_mul_f32 v[62:63], v[24:25], v[62:63]
	global_store_dwordx4 v[36:37], v[62:65], off offset:-1024 nt
	s_waitcnt vmcnt(16)
	s_nop 0
	v_lshlrev_b32_e32 v62, 16, v88
	v_and_b32_e32 v63, 0xffff0000, v88
	v_lshlrev_b32_e32 v64, 16, v89
	v_and_b32_e32 v65, 0xffff0000, v89
	v_pk_mul_f32 v[62:63], v[92:93], v[62:63] op_sel_hi:[0,1]
	v_pk_mul_f32 v[64:65], v[92:93], v[64:65] op_sel_hi:[0,1]
	v_pk_mul_f32 v[64:65], v[30:31], v[64:65]
	v_pk_mul_f32 v[62:63], v[28:29], v[62:63]
	global_store_dwordx4 v[36:37], v[62:65], off nt
	s_cbranch_scc1 .LBB0_1217
; __global__ void __launch_bounds__(512, 2) fwd_megakernel(Args a) {
;     ...
;             if (has2) {
; #pragma unroll
;                 for (int j = 0; j < 8; ++j) { const f32x4 v = (f32x4){pg8::bf_lo(z[j].x), pg8::bf_hi(z[j].x), pg8::bf_lo(z[j].y), pg8::bf_hi(z[j].y)}; orow2[lane + 64 * j] = v * rt * gv[j]; } }
	s_waitcnt vmcnt(16)
	v_fmamk_f32 v61, v61, 0x3a000000, v32
	v_rsq_f32_e32 v66, v61
	s_lshl_b64 s[10:11], s[10:11], 11
	s_lshl_b64 s[10:11], s[10:11], 2
	s_waitcnt vmcnt(15)
	v_lshlrev_b32_e32 v62, 16, v54
	v_and_b32_e32 v63, 0xffff0000, v54
	v_lshlrev_b32_e32 v54, 16, v55
	v_and_b32_e32 v55, 0xffff0000, v55
	s_add_u32 s10, s30, s10
	v_pk_mul_f32 v[62:63], v[66:67], v[62:63] op_sel_hi:[0,1]
	v_pk_mul_f32 v[54:55], v[66:67], v[54:55] op_sel_hi:[0,1]
	s_addc_u32 s11, s31, s11
	v_pk_mul_f32 v[64:65], v[2:3], v[54:55]
	v_pk_mul_f32 v[62:63], v[0:1], v[62:63]
	s_waitcnt vmcnt(14)
	v_lshlrev_b32_e32 v54, 16, v52
	v_and_b32_e32 v55, 0xffff0000, v52
	v_lshlrev_b32_e32 v52, 16, v53
	v_and_b32_e32 v53, 0xffff0000, v53
	global_store_dwordx4 v56, v[62:65], s[10:11] nt
	v_pk_mul_f32 v[52:53], v[66:67], v[52:53] op_sel_hi:[0,1]
	s_nop 0
	v_pk_mul_f32 v[62:63], v[66:67], v[54:55] op_sel_hi:[0,1]
	v_pk_mul_f32 v[54:55], v[6:7], v[52:53]
	v_pk_mul_f32 v[52:53], v[4:5], v[62:63]
	global_store_dwordx4 v56, v[52:55], s[10:11] offset:1024 nt
	s_waitcnt vmcnt(15)
	s_nop 0
	v_lshlrev_b32_e32 v52, 16, v50
	v_and_b32_e32 v53, 0xffff0000, v50
	v_lshlrev_b32_e32 v50, 16, v51
	v_and_b32_e32 v51, 0xffff0000, v51
	v_pk_mul_f32 v[54:55], v[66:67], v[52:53] op_sel_hi:[0,1]
	v_pk_mul_f32 v[50:51], v[66:67], v[50:51] op_sel_hi:[0,1]
	v_pk_mul_f32 v[52:53], v[10:11], v[50:51]
	v_pk_mul_f32 v[50:51], v[8:9], v[54:55]
	global_store_dwordx4 v56, v[50:53], s[10:11] offset:2048 nt
	s_waitcnt vmcnt(15)
	s_nop 0
	v_lshlrev_b32_e32 v50, 16, v48
	v_and_b32_e32 v51, 0xffff0000, v48
	v_lshlrev_b32_e32 v48, 16, v49
	v_and_b32_e32 v49, 0xffff0000, v49
	v_pk_mul_f32 v[52:53], v[66:67], v[50:51] op_sel_hi:[0,1]
	v_pk_mul_f32 v[48:49], v[66:67], v[48:49] op_sel_hi:[0,1]
	v_pk_mul_f32 v[50:51], v[14:15], v[48:49]
	v_pk_mul_f32 v[48:49], v[12:13], v[52:53]
	global_store_dwordx4 v56, v[48:51], s[10:11] offset:3072 nt
	s_waitcnt vmcnt(15)
	s_nop 0
	v_lshlrev_b32_e32 v48, 16, v46
	v_and_b32_e32 v49, 0xffff0000, v46
	v_lshlrev_b32_e32 v46, 16, v47
	v_and_b32_e32 v47, 0xffff0000, v47
	v_pk_mul_f32 v[50:51], v[66:67], v[48:49] op_sel_hi:[0,1]
	v_pk_mul_f32 v[46:47], v[66:67], v[46:47] op_sel_hi:[0,1]
	v_pk_mul_f32 v[48:49], v[18:19], v[46:47]
	v_pk_mul_f32 v[46:47], v[16:17], v[50:51]
	global_store_dwordx4 v57, v[46:49], s[10:11] nt
	s_waitcnt vmcnt(15)
	s_nop 0
	v_lshlrev_b32_e32 v46, 16, v44
	v_and_b32_e32 v47, 0xffff0000, v44
	v_lshlrev_b32_e32 v44, 16, v45
	v_and_b32_e32 v45, 0xffff0000, v45
	v_pk_mul_f32 v[48:49], v[66:67], v[46:47] op_sel_hi:[0,1]
	v_pk_mul_f32 v[44:45], v[66:67], v[44:45] op_sel_hi:[0,1]
	v_pk_mul_f32 v[46:47], v[22:23], v[44:45]
	v_pk_mul_f32 v[44:45], v[20:21], v[48:49]
	global_store_dwordx4 v58, v[44:47], s[10:11] nt
	s_waitcnt vmcnt(15)
	s_nop 0
	v_lshlrev_b32_e32 v44, 16, v42
	v_and_b32_e32 v45, 0xffff0000, v42
	v_lshlrev_b32_e32 v42, 16, v43
	v_and_b32_e32 v43, 0xffff0000, v43
	v_pk_mul_f32 v[46:47], v[66:67], v[44:45] op_sel_hi:[0,1]
	v_pk_mul_f32 v[42:43], v[66:67], v[42:43] op_sel_hi:[0,1]
	v_pk_mul_f32 v[44:45], v[26:27], v[42:43]
	v_pk_mul_f32 v[42:43], v[24:25], v[46:47]
	global_store_dwordx4 v59, v[42:45], s[10:11] nt
	s_waitcnt vmcnt(15)
	s_nop 0
	v_lshlrev_b32_e32 v42, 16, v40
	v_and_b32_e32 v43, 0xffff0000, v40
	v_lshlrev_b32_e32 v40, 16, v41
	v_and_b32_e32 v41, 0xffff0000, v41
	v_pk_mul_f32 v[44:45], v[66:67], v[42:43] op_sel_hi:[0,1]
	v_pk_mul_f32 v[40:41], v[66:67], v[40:41] op_sel_hi:[0,1]
	v_pk_mul_f32 v[42:43], v[30:31], v[40:41]
	v_pk_mul_f32 v[40:41], v[28:29], v[44:45]
	global_store_dwordx4 v60, v[40:43], s[10:11] nt
	s_branch .LBB0_1217
